# HGRN2 chunk loop: batched LDS reads with counted waits, no store waits in loop, loads kept in flight, scalar-base addressing, V tile remap to avoid LDS bank conflicts
# speedup vs baseline: 1.0222x; 1.0125x over previous
.LBB0_928:
	s_or_b64 exec, exec, s[0:1]
	v_mov_b32_e32 v2, s35
	s_waitcnt lgkmcnt(0)
	s_barrier
	ds_read_b32 v2, v2
	s_waitcnt lgkmcnt(0)
	v_readfirstlane_b32 s3, v2
	s_cmp_ge_i32 s3, s5
	s_cbranch_scc1 .LBB0_1012
	s_add_u32 s16, s14, 0x2c600000
	s_addc_u32 s17, s15, 0
	s_add_u32 s36, s14, 0x32600000
	s_addc_u32 s37, s15, 0
	v_ashrrev_i32_e32 v6, 4, v0
	s_add_u32 s0, s14, 0x36e00000
	v_writelane_b32 v255, s18, 24
	s_addc_u32 s1, s15, 0
	s_waitcnt vmcnt(0)
	v_lshlrev_b32_e32 v54, 2, v6
	v_writelane_b32 v255, s19, 25
	s_add_u32 s18, s14, 0x4ee00000
	v_ashrrev_i32_e32 v55, 31, v54
	s_addc_u32 s19, s15, 0
	v_lshlrev_b64 v[70:71], 9, v[54:55]
	s_mov_b64 s[14:15], 0x4000
	v_lshl_add_u64 v[86:87], v[70:71], 0, s[14:15]
	s_mov_b64 s[14:15], 0x4200
	v_lshl_add_u64 v[88:89], v[70:71], 0, s[14:15]
	s_mov_b64 s[14:15], 0x4400
	v_lshl_add_u64 v[90:91], v[70:71], 0, s[14:15]
	s_mov_b64 s[14:15], 0x4600
	v_lshl_add_u64 v[92:93], v[70:71], 0, s[14:15]
	s_mov_b64 s[14:15], 0x6000
	v_lshl_add_u64 v[94:95], v[70:71], 0, s[14:15]
	s_mov_b64 s[14:15], 0x6200
	v_lshl_add_u64 v[96:97], v[70:71], 0, s[14:15]
	s_mov_b64 s[14:15], 0x6400
	v_lshl_add_u64 v[98:99], v[70:71], 0, s[14:15]
	s_mov_b64 s[14:15], 0x6600
	v_lshl_add_u64 v[100:101], v[70:71], 0, s[14:15]
	s_mov_b64 s[14:15], 0x8000
	v_lshl_add_u64 v[102:103], v[70:71], 0, s[14:15]
	s_mov_b64 s[14:15], 0x8200
	v_lshl_add_u64 v[104:105], v[70:71], 0, s[14:15]
	s_mov_b64 s[14:15], 0x8400
	v_lshl_add_u64 v[106:107], v[70:71], 0, s[14:15]
	s_mov_b64 s[14:15], 0x8600
	v_lshl_add_u64 v[108:109], v[70:71], 0, s[14:15]
	s_mov_b64 s[14:15], 0xa000
	v_lshl_add_u64 v[110:111], v[70:71], 0, s[14:15]
	s_mov_b64 s[14:15], 0xa200
	v_lshl_add_u64 v[112:113], v[70:71], 0, s[14:15]
	s_mov_b64 s[14:15], 0xa400
	v_lshl_add_u64 v[114:115], v[70:71], 0, s[14:15]
	s_mov_b64 s[14:15], 0xa600
	v_lshl_add_u64 v[116:117], v[70:71], 0, s[14:15]
	s_mov_b64 s[14:15], 0xc000
	v_lshl_add_u64 v[118:119], v[70:71], 0, s[14:15]
	s_mov_b64 s[14:15], 0xc200
	v_lshl_add_u64 v[120:121], v[70:71], 0, s[14:15]
	s_mov_b64 s[14:15], 0xc400
	v_lshl_add_u64 v[122:123], v[70:71], 0, s[14:15]
	s_mov_b64 s[14:15], 0xc600
	v_lshl_add_u64 v[124:125], v[70:71], 0, s[14:15]
	s_mov_b64 s[14:15], 0xe000
	v_lshl_add_u64 v[126:127], v[70:71], 0, s[14:15]
	s_mov_b64 s[14:15], 0xe200
	s_lshl_b32 s20, s2, 4
	v_lshl_add_u64 v[128:129], v[70:71], 0, s[14:15]
	s_mov_b64 s[14:15], 0xe400
	s_ashr_i32 s21, s20, 31
	v_lshl_add_u64 v[130:131], v[70:71], 0, s[14:15]
	s_mov_b64 s[14:15], 0xe600
	v_or_b32_e32 v56, 1, v54
	v_lshl_add_u64 v[132:133], v[70:71], 0, s[14:15]
	v_lshlrev_b32_e32 v2, 2, v0
	s_lshl_b64 s[14:15], s[20:21], 2
	v_and_b32_e32 v50, 15, v0
	v_or_b32_e32 v58, 2, v54
	v_ashrrev_i32_e32 v57, 31, v56
	v_and_b32_e32 v51, 15, v0
	v_subrev_u32_e32 v1, 64, v2
	v_cmp_lt_i32_e32 vcc, 15, v0
	s_add_u32 s12, s12, s14
	v_lshlrev_b64 v[72:73], 9, v[56:57]
	v_ashrrev_i32_e32 v59, 31, v58
	v_cndmask_b32_e32 v57, v2, v1, vcc
	v_add_u32_e32 v1, 0xffffff80, v2
	v_cmp_lt_i32_e32 vcc, 31, v0
	v_lshlrev_b32_e32 v4, 2, v50
	s_addc_u32 s13, s13, s15
	v_mov_b32_e32 v5, v3
	v_or_b32_e32 v52, s20, v50
	v_lshlrev_b64 v[74:75], 9, v[58:59]
	v_not_b32_e32 v53, v51
	v_cndmask_b32_e32 v59, v2, v1, vcc
	v_cmp_gt_u32_e64 s[44:45], 16, v0
	v_and_b32_e32 v155, -16, v0
	v_lshl_add_u64 v[0:1], s[12:13], 0, v[4:5]
	s_mov_b64 s[12:13], 0x6480000
	s_movk_i32 s2, 0x220
	v_lshl_add_u64 v[138:139], v[0:1], 0, s[12:13]
	v_mad_u64_u32 v[140:141], s[12:13], v6, s2, v[52:53]
	s_movk_i32 s2, 0x88
	v_mad_u64_u32 v[142:143], s[12:13], v56, s2, v[52:53]
	v_add_u32_e32 v62, 16, v54
	s_waitcnt vmcnt(1)
	v_add_u32_e32 v66, 18, v54
	v_readlane_b32 s12, v254, 19
	v_or_b32_e32 v60, 3, v54
	v_add_u32_e32 v64, 17, v54
	v_add_u32_e32 v68, 19, v54
	v_ashrrev_i32_e32 v63, 31, v62
	v_ashrrev_i32_e32 v67, 31, v66
	v_add_u32_e32 v134, s20, v54
	v_readlane_b32 s13, v254, 20
	s_add_u32 s12, s12, s14
	v_ashrrev_i32_e32 v61, 31, v60
	v_lshlrev_b64 v[78:79], 9, v[62:63]
	v_ashrrev_i32_e32 v65, 31, v64
	v_lshlrev_b64 v[82:83], 9, v[66:67]
	v_ashrrev_i32_e32 v69, 31, v68
	v_mul_lo_u32 v63, v52, 48
	v_mad_u32_u24 v67, v134, 24, v51
	v_lshlrev_b32_e32 v2, 1, v134
	v_lshlrev_b32_e32 v154, 3, v6
	v_xor_b32_e32 v158, -2, v54
	v_xor_b32_e32 v160, -3, v54
	v_xor_b32_e32 v162, -4, v54
	v_add_u32_e32 v171, 0x88, v142
	v_add_u32_e32 v173, 0x110, v142
	v_sub_u32_e32 v0, v50, v54
	s_addc_u32 s13, s13, s15
	v_lshlrev_b64 v[76:77], 9, v[60:61]
	v_lshlrev_b64 v[80:81], 9, v[64:65]
	v_lshlrev_b64 v[84:85], 9, v[68:69]
	v_add_u32_e32 v55, 16, v51
	v_cmp_lt_i32_e64 s[40:41], 0, v6
	v_cmp_lt_i32_e64 s[42:43], 1, v6
	v_or_b32_e32 v61, 0xc0, v4
	v_lshl_add_u32 v65, v52, 2, 0
	v_lshl_add_u32 v69, v67, 1, 0
	v_lshl_add_u64 v[136:137], s[0:1], 0, v[2:3]
	v_mul_u32_u24_e32 v135, 0x88, v50
	v_cmp_gt_i32_e64 s[46:47], 2, v6
	v_mul_u32_u24_e32 v156, 48, v50
	v_sub_u32_e32 v157, 0xff, v54
	v_add_u32_e32 v159, 0x100, v158
	v_add_u32_e32 v161, 0x100, v160
	v_add_u32_e32 v163, 0x100, v162
	v_sub_u32_e32 v164, 0xff, v51
	v_sub_u32_e32 v165, 0xef, v54
	v_sub_u32_e32 v166, 0xee, v54
	v_sub_u32_e32 v167, 0xed, v54
	v_sub_u32_e32 v168, 0xec, v54
	v_sub_u32_e32 v169, 0xef, v51
	v_lshl_add_u32 v141, v140, 1, 0
	v_add3_u32 v170, 0, v63, v154
	v_lshl_add_u32 v143, v142, 1, 0
	v_lshl_add_u32 v172, v171, 1, 0
	v_lshl_add_u32 v174, v173, 1, 0
	v_cmp_gt_i32_e64 s[48:49], 0, v0
	v_cmp_gt_i32_e64 s[50:51], 1, v0
	v_cmp_gt_i32_e64 s[52:53], 2, v0
	v_cmp_gt_i32_e64 s[54:55], 3, v0
	v_not_b32_e32 v175, v54
	v_lshl_add_u64 v[144:145], s[12:13], 0, v[4:5]
	v_sub_u32_e32 v176, 0, v154
	v_add_u32_e32 v177, 32, v51
	v_sub_u32_e32 v178, 0xdf, v51
	v_sub_u32_e32 v179, 0xdf, v54
	v_sub_u32_e32 v180, 0xffffffdf, v51
	v_sub_u32_e32 v181, 0xffffffdf, v54
	s_branch .LBB0_933

.LBB0_940:
	s_sub_i32 s4, s15, 64
	s_lshr_b32 s35, s4, 5
	s_lshl_b32 s4, s35, 8
	s_lshl_b32 s60, s14, 1
	s_add_u32 s13, s16, s60
	s_addc_u32 s25, s17, 0
	s_add_u32 s24, s13, 0x7800000
	s_addc_u32 s25, s25, 0
	s_cmp_eq_u32 s3, 0
	s_cselect_b64 vcc, -1, 0
	v_cndmask_b32_e32 v0, v157, v54, vcc
	v_add_u32_e32 v0, s4, v0
	v_ashrrev_i32_e32 v1, 31, v0
	v_ashrrev_i32_e32 v47, 31, v46
	v_lshlrev_b64 v[0:1], 11, v[0:1]
	v_lshl_add_u64 v[0:1], v[0:1], 0, v[46:47]
	v_lshlrev_b64 v[0:1], 1, v[0:1]
	v_lshl_add_u64 v[8:9], s[24:25], 0, v[0:1]
	v_lshl_add_u64 v[10:11], s[36:37], 0, v[0:1]
	v_cndmask_b32_e32 v0, v159, v56, vcc
	v_add_u32_e32 v0, s4, v0
	v_ashrrev_i32_e32 v1, 31, v0
	global_load_ushort v8, v[8:9], off
	v_lshlrev_b64 v[0:1], 11, v[0:1]
	v_lshl_add_u64 v[0:1], v[0:1], 0, v[46:47]
	v_lshlrev_b64 v[0:1], 1, v[0:1]
	v_lshl_add_u64 v[12:13], s[24:25], 0, v[0:1]
	global_load_ushort v12, v[12:13], off
	v_lshl_add_u64 v[14:15], s[36:37], 0, v[0:1]
	v_cndmask_b32_e32 v0, v161, v58, vcc
	v_add_u32_e32 v0, s4, v0
	v_ashrrev_i32_e32 v1, 31, v0
	v_lshlrev_b64 v[0:1], 11, v[0:1]
	v_lshl_add_u64 v[0:1], v[0:1], 0, v[46:47]
	v_lshlrev_b64 v[0:1], 1, v[0:1]
	v_lshl_add_u64 v[18:19], s[24:25], 0, v[0:1]
	v_lshl_add_u64 v[20:21], s[36:37], 0, v[0:1]
	v_cndmask_b32_e32 v0, v163, v60, vcc
	v_add_u32_e32 v0, s4, v0
	v_ashrrev_i32_e32 v1, 31, v0
	v_lshlrev_b64 v[0:1], 11, v[0:1]
	v_lshl_add_u64 v[0:1], v[0:1], 0, v[46:47]
	v_lshlrev_b64 v[0:1], 1, v[0:1]
	v_lshl_add_u64 v[6:7], s[24:25], 0, v[0:1]
	global_load_ushort v6, v[6:7], off
	v_cmp_eq_f32_e64 s[58:59], 0, v183
	v_lshl_add_u64 v[4:5], s[36:37], 0, v[0:1]
	v_cndmask_b32_e32 v0, v164, v51, vcc
	v_add_u32_e32 v0, s4, v0
	v_ashrrev_i32_e32 v1, 31, v0
	v_lshlrev_b64 v[0:1], 12, v[0:1]
	v_lshl_add_u64 v[0:1], s[0:1], 0, v[0:1]
	s_lshl_b32 s62, s12, 1
	v_lshl_add_u64 v[0:1], v[0:1], 0, s[62:63]
	v_lshlrev_b32_e32 v2, 1, v134
	v_lshl_add_u64 v[0:1], v[0:1], 0, v[2:3]
	global_load_dwordx2 v[0:1], v[0:1], off
	s_waitcnt vmcnt(3)
	v_lshlrev_b32_e32 v9, 16, v8
	v_mul_f32_e32 v9, 0xbfb8aa3b, v9
	v_exp_f32_e32 v9, v9
	global_load_ushort v8, v[10:11], off
	s_waitcnt vmcnt(3)
	v_lshlrev_b32_e32 v13, 16, v12
	v_min_f32_e32 v9, 0x7149f2ca, v9
	v_mul_f32_e32 v13, 0xbfb8aa3b, v13
	v_fma_f32 v16, v183, v9, 1.0
	v_exp_f32_e32 v13, v13
	global_load_ushort v12, v[14:15], off
	v_add_f32_e32 v10, 1.0, v9
	v_rcp_f32_e32 v11, v16
	v_rcp_f32_e32 v17, v10
	v_min_f32_e32 v13, 0x7149f2ca, v13
	v_add_f32_e32 v14, 1.0, v13
	v_cndmask_b32_e64 v11, v11, 1.0, s[58:59]
	v_fma_f32 v13, v183, v13, 1.0
	v_mul_f32_e32 v9, v16, v17
	v_mul_f32_e32 v11, v10, v11
	v_fma_f32 v10, -v16, v17, 1.0
	v_rcp_f32_e32 v17, v13
	v_rcp_f32_e32 v15, v14
	global_load_ushort v4, v[4:5], off
	s_waitcnt vmcnt(4)
	v_lshlrev_b32_e32 v6, 16, v6
	v_cndmask_b32_e64 v17, v17, 1.0, s[58:59]
	v_mul_f32_e32 v17, v14, v17
	global_load_ushort v14, v[18:19], off
	v_mul_f32_e32 v16, v13, v15
	v_fma_f32 v13, -v13, v15, 1.0
	v_mul_f32_e32 v5, 0xbfb8aa3b, v6
	v_exp_f32_e32 v5, v5
	v_mul_f32_e32 v17, v11, v17
	v_min_f32_e32 v5, 0x7149f2ca, v5
	v_add_f32_e32 v6, 1.0, v5
	v_fma_f32 v5, v183, v5, 1.0
	v_rcp_f32_e32 v7, v6
	s_waitcnt vmcnt(3)
	v_lshlrev_b32_e32 v8, 16, v8
	v_mul_f32_e32 v22, v5, v7
	s_waitcnt vmcnt(2)
	v_lshlrev_b32_e32 v12, 16, v12
	s_waitcnt vmcnt(1)
	v_lshlrev_b32_e32 v4, 16, v4
	s_waitcnt vmcnt(0)
	v_lshlrev_b32_e32 v15, 16, v14
	v_mul_f32_e32 v15, 0xbfb8aa3b, v15
	v_exp_f32_e32 v15, v15
	global_load_ushort v14, v[20:21], off
	v_min_f32_e32 v15, 0x7149f2ca, v15
	v_add_f32_e32 v18, 1.0, v15
	v_fma_f32 v15, v183, v15, 1.0
	v_rcp_f32_e32 v21, v15
	v_rcp_f32_e32 v19, v18
	v_cndmask_b32_e64 v21, v21, 1.0, s[58:59]
	v_mul_f32_e32 v21, v18, v21
	v_rcp_f32_e32 v18, v5
	v_fma_f32 v5, -v5, v7, 1.0
	v_mul_f32_e32 v20, v15, v19
	v_fma_f32 v15, -v15, v19, 1.0
	v_cndmask_b32_e64 v18, v18, 1.0, s[58:59]
	v_mul_f32_e32 v23, v6, v18
	v_cndmask_b32_e32 v6, v165, v62, vcc
	v_add_u32_e32 v6, s4, v6
	v_ashrrev_i32_e32 v7, 31, v6
	v_lshlrev_b64 v[6:7], 11, v[6:7]
	v_lshl_add_u64 v[6:7], v[6:7], 0, v[46:47]
	v_lshlrev_b64 v[6:7], 1, v[6:7]
	v_lshl_add_u64 v[18:19], s[24:25], 0, v[6:7]
	v_lshl_add_u64 v[6:7], s[36:37], 0, v[6:7]
	global_load_ushort v45, v[18:19], off
	global_load_ushort v44, v[6:7], off
	v_cndmask_b32_e32 v6, v166, v64, vcc
	v_add_u32_e32 v6, s4, v6
	v_ashrrev_i32_e32 v7, 31, v6
	v_lshlrev_b64 v[6:7], 11, v[6:7]
	v_lshl_add_u64 v[6:7], v[6:7], 0, v[46:47]
	v_lshlrev_b64 v[6:7], 1, v[6:7]
	v_lshl_add_u64 v[18:19], s[24:25], 0, v[6:7]
	v_lshl_add_u64 v[6:7], s[36:37], 0, v[6:7]
	global_load_ushort v43, v[18:19], off
	global_load_ushort v42, v[6:7], off
	v_cndmask_b32_e32 v6, v167, v66, vcc
	v_add_u32_e32 v6, s4, v6
	v_ashrrev_i32_e32 v7, 31, v6
	v_lshlrev_b64 v[6:7], 11, v[6:7]
	v_lshl_add_u64 v[6:7], v[6:7], 0, v[46:47]
	v_lshlrev_b64 v[6:7], 1, v[6:7]
	v_lshl_add_u64 v[18:19], s[24:25], 0, v[6:7]
	v_lshl_add_u64 v[6:7], s[36:37], 0, v[6:7]
	global_load_ushort v41, v[18:19], off
	global_load_ushort v40, v[6:7], off
	v_cndmask_b32_e32 v6, v168, v68, vcc
	v_add_u32_e32 v6, s4, v6
	v_ashrrev_i32_e32 v7, 31, v6
	v_lshlrev_b64 v[6:7], 11, v[6:7]
	v_lshl_add_u64 v[6:7], v[6:7], 0, v[46:47]
	v_lshlrev_b64 v[6:7], 1, v[6:7]
	v_lshl_add_u64 v[18:19], s[24:25], 0, v[6:7]
	v_lshl_add_u64 v[6:7], s[36:37], 0, v[6:7]
	global_load_ushort v39, v[18:19], off
	global_load_ushort v38, v[6:7], off
	v_cndmask_b32_e32 v6, v169, v55, vcc
	v_add_u32_e32 v6, s4, v6
	v_ashrrev_i32_e32 v7, 31, v6
	v_lshlrev_b64 v[6:7], 12, v[6:7]
	v_lshl_add_u64 v[6:7], s[0:1], 0, v[6:7]
	v_lshl_add_u64 v[6:7], v[6:7], 0, s[62:63]
	v_lshl_add_u64 v[6:7], v[6:7], 0, v[2:3]
	global_load_dwordx2 v[36:37], v[6:7], off
	v_mul_f32_e32 v6, v9, v16
	v_mul_f32_e32 v7, v6, v20
	v_mul_f32_e32 v16, v7, v22
	v_mul_f32_e32 v18, v17, v21
	v_mul_f32_e32 v19, v18, v23
	ds_bpermute_b32 v2, v57, v16
	ds_bpermute_b32 v20, v57, v19
	s_waitcnt lgkmcnt(1)
	v_mul_f32_e32 v2, v16, v2
	v_cndmask_b32_e64 v2, v16, v2, s[40:41]
	s_waitcnt lgkmcnt(0)
	v_mul_f32_e32 v20, v19, v20
	v_cndmask_b32_e64 v20, v19, v20, s[40:41]
	ds_bpermute_b32 v21, v59, v2
	ds_bpermute_b32 v22, v59, v20
	s_waitcnt vmcnt(9)
	v_lshlrev_b32_e32 v14, 16, v14
	s_waitcnt lgkmcnt(1)
	v_mul_f32_e32 v21, v2, v21
	v_cndmask_b32_e64 v2, v2, v21, s[42:43]
	s_waitcnt lgkmcnt(0)
	v_mul_f32_e32 v21, v20, v22
	v_cndmask_b32_e64 v20, v20, v21, s[42:43]
	ds_bpermute_b32 v21, v57, v2
	ds_bpermute_b32 v20, v57, v20
	ds_bpermute_b32 v2, v61, v2
	s_waitcnt lgkmcnt(2)
	v_cndmask_b32_e64 v21, 1.0, v21, s[40:41]
	s_waitcnt lgkmcnt(1)
	v_cndmask_b32_e64 v20, 1.0, v20, s[40:41]
	v_mul_f32_e32 v11, v11, v20
	v_mul_f32_e32 v9, v9, v21
	v_min_f32_e32 v11, 0x799a130c, v11
	v_mul_f32_e32 v8, v9, v8
	v_mul_f32_e32 v10, v10, v11
	v_cvt_pk_bf16_f32 v8, v8, s0
	ds_write_b16 v141, v8
	v_cvt_pk_bf16_f32 v8, v10, s0
	ds_write_b16 v141, v8 offset:4352
	s_waitcnt lgkmcnt(2)
	v_mul_f32_e32 v8, v10, v2
	v_cvt_pk_bf16_f32 v8, v8, s0
	ds_write_b16 v170, v8 offset:8704
	v_mul_f32_e32 v8, v17, v20
	v_mul_f32_e32 v6, v6, v21
	v_min_f32_e32 v8, 0x799a130c, v8
	v_mul_f32_e32 v6, v6, v12
	v_mul_f32_e32 v8, v13, v8
	v_cvt_pk_bf16_f32 v6, v6, s0
	ds_write_b16 v143, v6
	v_cvt_pk_bf16_f32 v6, v8, s0
	ds_write_b16 v143, v6 offset:4352
	v_mul_f32_e32 v6, v8, v2
	v_cvt_pk_bf16_f32 v6, v6, s0
	ds_write_b16 v170, v6 offset:8706
	v_mul_f32_e32 v6, v18, v20
	v_mul_f32_e32 v7, v7, v21
	v_min_f32_e32 v6, 0x799a130c, v6
	v_mul_f32_e32 v7, v7, v14
	v_mul_f32_e32 v6, v15, v6
	v_cvt_pk_bf16_f32 v7, v7, s0
	ds_write_b16 v172, v7
	v_cvt_pk_bf16_f32 v7, v6, s0
	v_mul_f32_e32 v6, v6, v2
	v_cvt_pk_bf16_f32 v6, v6, s0
	ds_write_b16 v172, v7 offset:4352
	ds_write_b16 v170, v6 offset:8708
	v_mul_f32_e32 v6, v19, v20
	v_min_f32_e32 v6, 0x799a130c, v6
	v_mul_f32_e32 v5, v5, v6
	v_mul_f32_e32 v6, v16, v21
	v_mul_f32_e32 v4, v6, v4
	v_cvt_pk_bf16_f32 v4, v4, s0
	ds_write_b16 v174, v4
	v_cvt_pk_bf16_f32 v4, v5, s0
	ds_write_b16 v174, v4 offset:4352
	v_mul_f32_e32 v4, v5, v2
	v_cvt_pk_bf16_f32 v4, v4, s0
	ds_write_b16 v170, v4 offset:8710
	s_and_saveexec_b64 s[12:13], s[44:45]
	ds_write_b32 v65, v2 offset:20992
	s_or_b64 exec, exec, s[12:13]
	s_add_u32 s12, s18, s60
	s_addc_u32 s13, s19, 0
	s_add_u32 s60, s12, s62
	s_addc_u32 s61, s13, 0
	s_lshl_b64 s[12:13], s[20:21], 1
	s_add_u32 s12, s60, s12
	s_addc_u32 s13, s61, s13
	v_lshlrev_b32_e32 v2, 1, v50
	v_mov_b32_e32 v148, 0
	v_lshl_add_u64 v[48:49], v[136:137], 0, s[62:63]
	v_lshl_add_u64 v[146:147], s[12:13], 0, v[2:3]
	s_mov_b32 s60, 0
	v_mov_b32_e32 v197, v179
	v_mov_b32_e32 v198, v178
	s_mov_b32 s61, 0
	v_mov_b32_e32 v149, v148
	v_mov_b32_e32 v150, v148
	v_mov_b32_e32 v151, v148
	v_mov_b32_e32 v4, v148
	v_mov_b32_e32 v5, v148
	v_mov_b32_e32 v6, v148
	v_mov_b32_e32 v7, v148
	v_mov_b32_e32 v8, v148
	v_mov_b32_e32 v9, v148
	v_mov_b32_e32 v10, v148
	v_mov_b32_e32 v11, v148
	v_mov_b32_e32 v12, v148
	v_mov_b32_e32 v13, v148
	v_mov_b32_e32 v14, v148
	v_mov_b32_e32 v15, v148
	v_mov_b32_e32 v16, v148
	v_mov_b32_e32 v17, v148
	v_mov_b32_e32 v18, v148
	v_mov_b32_e32 v19, v148
	v_mov_b32_e32 v20, v148
	v_mov_b32_e32 v21, v148
	v_mov_b32_e32 v22, v148
	v_mov_b32_e32 v23, v148
	v_mov_b32_e32 v24, v148
	v_mov_b32_e32 v25, v148
	v_mov_b32_e32 v26, v148
	v_mov_b32_e32 v27, v148
	v_mov_b32_e32 v28, v148
	v_mov_b32_e32 v29, v148
	v_mov_b32_e32 v30, v148
	v_mov_b32_e32 v31, v148
	v_mov_b32_e32 v32, v148
	v_mov_b32_e32 v33, v148
	v_mov_b32_e32 v34, v148
	v_mov_b32_e32 v35, v148
	ds_write_b16 v69, v0 offset:14848
	ds_write_b16_d16_hi v69, v0 offset:14896
	ds_write_b16 v69, v1 offset:14944
	ds_write_b16_d16_hi v69, v1 offset:14992
	v_mov_b32_e32 v208, 0
	v_mov_b32_e32 v209, 0
	v_mov_b32_e32 v210, 0
	v_mov_b32_e32 v211, 0
	v_mov_b32_e32 v212, 0x580
	v_mad_u32_u24 v207, v155, v212, v63
	s_and_saveexec_b64 s[12:13], s[46:47]
	ds_write_b128 v207, v[208:211] offset:8736
	s_or_b64 exec, exec, s[12:13]
	v_mov_b32_e32 v0, v54
	v_sub_u32_e32 v1, 255, v0
	v_cndmask_b32_e32 v0, v1, v0, vcc
	v_add_u32_e32 v0, s4, v0
	v_lshlrev_b32_e32 v0, 12, v0
	v_lshl_add_u32 v197, v46, 1, v0
	v_add_u32_e32 v0, 1, v54
	v_sub_u32_e32 v1, 255, v0
	v_cndmask_b32_e32 v0, v1, v0, vcc
	v_add_u32_e32 v0, s4, v0
	v_lshlrev_b32_e32 v0, 12, v0
	v_lshl_add_u32 v198, v46, 1, v0
	v_add_u32_e32 v0, 2, v54
	v_sub_u32_e32 v1, 255, v0
	v_cndmask_b32_e32 v0, v1, v0, vcc
	v_add_u32_e32 v0, s4, v0
	v_lshlrev_b32_e32 v0, 12, v0
	v_lshl_add_u32 v248, v46, 1, v0
	v_add_u32_e32 v0, 3, v54
	v_sub_u32_e32 v1, 255, v0
	v_cndmask_b32_e32 v0, v1, v0, vcc
	v_add_u32_e32 v0, s4, v0
	v_lshlrev_b32_e32 v0, 12, v0
	v_lshl_add_u32 v249, v46, 1, v0
	v_readfirstlane_b32 s100, v146
	v_readfirstlane_b32 s101, v147
	v_readfirstlane_b32 s32, v46
	s_lshl_b32 s32, s32, 1
	s_sub_u32 s100, s100, s32
	s_subb_u32 s101, s101, 0
	v_add_u32_e32 v0, 32, v51
	v_sub_u32_e32 v1, 255, v0
	v_cndmask_b32_e32 v0, v1, v0, vcc
	v_add_u32_e32 v0, s4, v0
	v_lshlrev_b32_e32 v0, 12, v0
	v_mov_b32_e32 v1, 0
	v_lshl_add_u64 v[48:49], v[0:1], 0, v[48:49]
	s_cmp_lg_u64 vcc, 0
	s_mov_b32 s32, 0x10000
	s_cselect_b32 s32, s32, 0xffff0000
	s_cbranch_scc0 .Lhg_bwd_c
	s_add_u32 s24, s24, 0x20000
	s_addc_u32 s25, s25, 0
	s_add_u32 s98, s36, 0x20000
	s_addc_u32 s99, s37, 0
	s_branch .Lhg_dir_c
.Lhg_bwd_c:
	s_sub_u32 s24, s24, 0x20000
	s_subb_u32 s25, s25, 0
	s_sub_u32 s98, s36, 0x20000
	s_subb_u32 s99, s37, 0
.Lhg_dir_c:
	v_mov_b32_e32 v46, s32
	v_ashrrev_i32_e32 v47, 31, v46
	s_waitcnt vmcnt(0) lgkmcnt(0)
	s_barrier
	s_bitcmp1_b32 s61, 0
	s_cselect_b32 s62, 0x5800, 0
	s_cmp_gt_u32 s61, 14
	s_cbranch_scc1 .LBB0_944
	s_branch .LBB0_945

.LBB0_945:
	s_cmpk_eq_i32 s60, 0xe0
	v_mov_b32_e32 v200, v44
	v_mov_b32_e32 v202, v42
	v_mov_b32_e32 v204, v40
	v_mov_b32_e32 v206, v38
	v_mov_b32_e32 v199, v45
	v_mov_b32_e32 v201, v43
	v_mov_b32_e32 v203, v41
	v_mov_b32_e32 v205, v39
	v_mov_b64_e32 v[152:153], v[36:37]
	s_cbranch_scc1 .LBB0_947
	global_load_ushort v199, v197, s[24:25]
	global_load_ushort v200, v197, s[98:99]
	global_load_ushort v201, v198, s[24:25]
	global_load_ushort v202, v198, s[98:99]
	global_load_ushort v203, v248, s[24:25]
	global_load_ushort v204, v248, s[98:99]
	global_load_ushort v205, v249, s[24:25]
	global_load_ushort v206, v249, s[98:99]
	global_load_dwordx2 v[152:153], v[48:49], off

.LBB0_950:
	v_lshlrev_b32_e32 v0, 1, v135
	v_lshlrev_b32_e32 v1, 1, v154
	v_add3_u32 v2, s62, v0, v1
	v_add_u32_e32 v207, s62, v63
	v_lshl_add_u32 v227, v54, 1, v207
	v_add_u32_e32 v0, v2, v176
	ds_read_b128 v[36:39], v2 offset:4352
	ds_read_b128 v[40:43], v2
	ds_read_b128 v[208:211], v2 offset:4416
	ds_read_b128 v[184:187], v2 offset:64
	ds_read_b128 v[212:215], v2 offset:4480
	ds_read_b128 v[228:231], v2 offset:128
	ds_read_b128 v[232:235], v2 offset:4544
	ds_read_b128 v[236:239], v2 offset:192
	ds_read_b64 v[188:189], v227 offset:14848
	ds_read2_b64 v[240:243], v0 offset1:4
	ds_read2_b64 v[244:247], v0 offset0:8 offset1:12
	s_and_b64 s[12:13], s[54:55], s[52:53]
	v_mov_b32_e32 v190, v3
	v_mov_b32_e32 v191, v3
	s_waitcnt lgkmcnt(9)
	v_mfma_f32_16x16x32_bf16 v[36:39], v[36:39], v[40:43], 0
	s_waitcnt lgkmcnt(7)
	v_mfma_f32_16x16x32_bf16 v[36:39], v[208:211], v[184:187], v[36:39]
	s_waitcnt lgkmcnt(5)
	v_mfma_f32_16x16x32_bf16 v[36:39], v[212:215], v[228:231], v[36:39]
	s_waitcnt lgkmcnt(3)
	v_mfma_f32_16x16x32_bf16 v[36:39], v[232:235], v[236:239], v[36:39]
	ds_read2_b64 v[208:211], v0 offset0:16 offset1:20
	ds_read2_b64 v[212:215], v0 offset0:24 offset1:28
	v_cvt_pk_bf16_f32 v184, v4, v5
	v_cvt_pk_bf16_f32 v185, v6, v7
	v_cvt_pk_bf16_f32 v186, v8, v9
	v_cvt_pk_bf16_f32 v187, v10, v11
	v_mov_b32_e32 v2, v3
	s_nop 0
	v_cndmask_b32_e64 v192, v38, 0, s[12:13]
	s_and_b64 s[12:13], s[12:13], s[50:51]
	v_cndmask_b32_e64 v0, v37, 0, s[12:13]
	s_and_b64 s[12:13], s[12:13], s[48:49]
	v_cndmask_b32_e64 v36, v36, 0, s[12:13]
	v_cndmask_b32_e64 v1, v39, 0, s[54:55]
	v_cvt_pk_bf16_f32 v0, v36, v0
	v_cvt_pk_bf16_f32 v1, v192, v1
	s_nop 0
	s_waitcnt lgkmcnt(4)
	v_mfma_f32_16x16x32_bf16 v[36:39], v[0:3], v[188:191], 0
	v_cvt_pk_bf16_f32 v40, v12, v13
	v_cvt_pk_bf16_f32 v41, v14, v15
	v_cvt_pk_bf16_f32 v42, v16, v17
	v_cvt_pk_bf16_f32 v43, v18, v19
	v_cvt_pk_bf16_f32 v228, v20, v21
	v_cvt_pk_bf16_f32 v229, v22, v23
	v_cvt_pk_bf16_f32 v230, v24, v25
	v_cvt_pk_bf16_f32 v231, v26, v27
	v_cvt_pk_bf16_f32 v232, v28, v29
	v_cvt_pk_bf16_f32 v233, v30, v31
	v_cvt_pk_bf16_f32 v234, v32, v33
	v_cvt_pk_bf16_f32 v235, v34, v35
	s_waitcnt lgkmcnt(3)
	v_mfma_f32_16x16x32_bf16 v[36:39], v[240:243], v[184:187], v[36:39]
	s_waitcnt lgkmcnt(2)
	v_mfma_f32_16x16x32_bf16 v[36:39], v[244:247], v[40:43], v[36:39]
	s_waitcnt lgkmcnt(1)
	v_mfma_f32_16x16x32_bf16 v[36:39], v[208:211], v[228:231], v[36:39]
	s_waitcnt lgkmcnt(0)
	v_mfma_f32_16x16x32_bf16 v[36:39], v[212:215], v[232:235], v[36:39]
	v_add_u32_e32 v227, v207, v155
	v_lshl_add_u32 v216, v54, 2, s62
	v_add3_u32 v217, s62, v155, v156
	v_mov_b32_e32 v32, 0
	v_mov_b32_e32 v33, 0
	v_mov_b32_e32 v34, 0
	v_mov_b32_e32 v35, 0
	s_and_saveexec_b64 s[12:13], s[46:47]
	ds_read_b128 v[32:35], v227 offset:14848
	s_or_b64 exec, exec, s[12:13]
	ds_read_b128 v[240:243], v216 offset:20992
	ds_read_b128 v[184:187], v217 offset:8704
	ds_read_b128 v[244:247], v216 offset:21056
	ds_read_b128 v[40:43], v217 offset:9472
	ds_read_b128 v[208:211], v216 offset:21120
	ds_read_b128 v[228:231], v217 offset:10240
	ds_read_b128 v[212:215], v216 offset:21184
	ds_read_b128 v[232:235], v217 offset:11008
	v_cvt_pk_bf16_f32 v192, v36, s0
	global_store_short v197, v192, s[100:101]
	v_cvt_pk_bf16_f32 v193, v37, s0
	global_store_short v198, v193, s[100:101]
	v_cvt_pk_bf16_f32 v192, v38, s0
	global_store_short v248, v192, s[100:101]
	v_cvt_pk_bf16_f32 v193, v39, s0
	global_store_short v249, v193, s[100:101]
	v_add_u32_e32 v197, s32, v197
	v_add_u32_e32 v198, s32, v198
	v_add_u32_e32 v248, s32, v248
	v_add_u32_e32 v249, s32, v249
	v_lshl_add_u64 v[48:49], v[48:49], 0, v[46:47]
	s_waitcnt lgkmcnt(6)
	v_pk_mul_f32 v[6:7], v[6:7], v[242:243]
	v_pk_mul_f32 v[4:5], v[4:5], v[240:241]
	s_nop 1
	v_mfma_f32_16x16x32_bf16 v[4:7], v[184:187], v[32:35], v[4:7]
	ds_read_b128 v[240:243], v216 offset:21248
	ds_read_b128 v[184:187], v217 offset:11776
	s_waitcnt lgkmcnt(6)
	v_pk_mul_f32 v[10:11], v[10:11], v[246:247]
	v_pk_mul_f32 v[8:9], v[8:9], v[244:245]
	s_nop 1
	v_mfma_f32_16x16x32_bf16 v[8:11], v[40:43], v[32:35], v[8:11]
	ds_read_b128 v[244:247], v216 offset:21312
	ds_read_b128 v[40:43], v217 offset:12544
	s_waitcnt lgkmcnt(6)
	v_pk_mul_f32 v[14:15], v[14:15], v[210:211]
	v_pk_mul_f32 v[12:13], v[12:13], v[208:209]
	s_nop 1
	v_mfma_f32_16x16x32_bf16 v[12:15], v[228:231], v[32:35], v[12:15]
	ds_read_b128 v[208:211], v216 offset:21376
	ds_read_b128 v[228:231], v217 offset:13312
	s_waitcnt lgkmcnt(6)
	v_pk_mul_f32 v[18:19], v[18:19], v[214:215]
	v_pk_mul_f32 v[16:17], v[16:17], v[212:213]
	s_nop 1
	v_mfma_f32_16x16x32_bf16 v[16:19], v[232:235], v[32:35], v[16:19]
	ds_read_b128 v[212:215], v216 offset:21440
	ds_read_b128 v[232:235], v217 offset:14080
	s_waitcnt lgkmcnt(6)
	v_pk_mul_f32 v[22:23], v[22:23], v[242:243]
	v_pk_mul_f32 v[20:21], v[20:21], v[240:241]
	s_nop 1
	v_mfma_f32_16x16x32_bf16 v[20:23], v[184:187], v[32:35], v[20:23]
	s_waitcnt lgkmcnt(4)
	v_pk_mul_f32 v[26:27], v[26:27], v[246:247]
	v_pk_mul_f32 v[24:25], v[24:25], v[244:245]
	s_nop 1
	v_mfma_f32_16x16x32_bf16 v[24:27], v[40:43], v[32:35], v[24:27]
	s_waitcnt lgkmcnt(2)
	v_pk_mul_f32 v[30:31], v[30:31], v[210:211]
	v_pk_mul_f32 v[28:29], v[28:29], v[208:209]
	s_nop 1
	v_mfma_f32_16x16x32_bf16 v[28:31], v[228:231], v[32:35], v[28:31]
	s_waitcnt lgkmcnt(0)
	v_pk_mul_f32 v[214:215], v[150:151], v[214:215]
	v_pk_mul_f32 v[212:213], v[148:149], v[212:213]
	s_nop 1
	v_mfma_f32_16x16x32_bf16 v[32:35], v[232:235], v[32:35], v[212:215]
	s_add_i32 s60, s60, 16
	s_add_i32 s61, s61, 1
	s_cmpk_lg_i32 s60, 0x100
	s_barrier
	s_cbranch_scc1 .LBB0_943
	s_mov_b64 s[58:59], -1
	s_branch .LBB0_1005

.LBB0_975:
	s_and_b64 s[56:57], s[12:13], exec
	s_cselect_b32 s4, 0x400, s31
	s_lshl_b32 s15, s35, 10
	s_addk_i32 s15, 0xd000
	s_lshl_b32 s56, s35, 8
	s_and_b64 s[12:13], s[12:13], exec
	s_cselect_b32 s60, s15, s56
	s_lshl_b32 s80, s14, 1
	s_add_u32 s12, s16, s80
	s_addc_u32 s13, s17, 0
	s_add_u32 s12, s12, 0x7800000
	s_addc_u32 s13, s13, 0
	s_cmp_eq_u32 s3, 0
	s_cselect_b64 vcc, -1, 0
	v_add_u32_e32 v0, s4, v175
	v_cndmask_b32_e32 v0, v0, v54, vcc
	v_add_u32_e32 v0, s60, v0
	v_ashrrev_i32_e32 v1, 31, v0
	v_ashrrev_i32_e32 v147, 31, v146
	v_lshlrev_b64 v[0:1], 11, v[0:1]
	v_lshl_add_u64 v[0:1], v[0:1], 0, v[146:147]
	v_lshlrev_b64 v[0:1], 1, v[0:1]
	v_lshl_add_u64 v[40:41], s[12:13], 0, v[0:1]
	v_lshl_add_u64 v[42:43], s[36:37], 0, v[0:1]
	v_add_u32_e32 v0, s4, v158
	v_cndmask_b32_e32 v0, v0, v56, vcc
	v_add_u32_e32 v0, s60, v0
	v_ashrrev_i32_e32 v1, 31, v0
	global_load_ushort v40, v[40:41], off
	v_lshlrev_b64 v[0:1], 11, v[0:1]
	v_lshl_add_u64 v[0:1], v[0:1], 0, v[146:147]
	v_lshlrev_b64 v[0:1], 1, v[0:1]
	v_lshl_add_u64 v[44:45], s[12:13], 0, v[0:1]
	global_load_ushort v44, v[44:45], off
	v_lshl_add_u64 v[46:47], s[36:37], 0, v[0:1]
	v_add_u32_e32 v0, s4, v160
	v_cndmask_b32_e32 v0, v0, v58, vcc
	v_add_u32_e32 v0, s60, v0
	v_ashrrev_i32_e32 v1, 31, v0
	v_lshlrev_b64 v[0:1], 11, v[0:1]
	v_lshl_add_u64 v[0:1], v[0:1], 0, v[146:147]
	v_lshlrev_b64 v[0:1], 1, v[0:1]
	v_lshl_add_u64 v[48:49], s[12:13], 0, v[0:1]
	s_waitcnt vmcnt(6)
	v_lshl_add_u64 v[148:149], s[36:37], 0, v[0:1]
	v_add_u32_e32 v0, s4, v162
	v_cndmask_b32_e32 v0, v0, v60, vcc
	v_add_u32_e32 v0, s60, v0
	v_ashrrev_i32_e32 v1, 31, v0
	v_lshlrev_b64 v[0:1], 11, v[0:1]
	v_lshl_add_u64 v[0:1], v[0:1], 0, v[146:147]
	v_lshlrev_b64 v[0:1], 1, v[0:1]
	v_lshl_add_u64 v[38:39], s[12:13], 0, v[0:1]
	global_load_ushort v38, v[38:39], off
	v_cmp_eq_f32_e64 s[56:57], 0, v183
	v_lshl_add_u64 v[36:37], s[36:37], 0, v[0:1]
	v_add_u32_e32 v0, s4, v53
	v_cndmask_b32_e32 v0, v0, v51, vcc
	v_add_u32_e32 v0, s60, v0
	v_ashrrev_i32_e32 v1, 31, v0
	v_lshlrev_b64 v[0:1], 12, v[0:1]
	v_lshl_add_u64 v[0:1], s[0:1], 0, v[0:1]
	s_lshl_b32 s62, s61, 1
	v_lshl_add_u64 v[0:1], v[0:1], 0, s[62:63]
	v_lshlrev_b32_e32 v2, 1, v134
	v_lshl_add_u64 v[0:1], v[0:1], 0, v[2:3]
	global_load_dwordx2 v[0:1], v[0:1], off
	s_waitcnt vmcnt(3)
	v_lshlrev_b32_e32 v41, 16, v40
	v_mul_f32_e32 v41, 0xbfb8aa3b, v41
	v_exp_f32_e32 v41, v41
	global_load_ushort v40, v[42:43], off
	s_waitcnt vmcnt(3)
	v_lshlrev_b32_e32 v45, 16, v44
	v_min_f32_e32 v41, 0x7149f2ca, v41
	v_mul_f32_e32 v45, 0xbfb8aa3b, v45
	v_fma_f32 v150, v183, v41, 1.0
	v_exp_f32_e32 v45, v45
	global_load_ushort v44, v[46:47], off
	v_add_f32_e32 v42, 1.0, v41
	v_rcp_f32_e32 v43, v150
	v_rcp_f32_e32 v151, v42
	v_min_f32_e32 v45, 0x7149f2ca, v45
	v_add_f32_e32 v46, 1.0, v45
	v_cndmask_b32_e64 v43, v43, 1.0, s[56:57]
	v_fma_f32 v45, v183, v45, 1.0
	v_mul_f32_e32 v41, v150, v151
	v_mul_f32_e32 v43, v42, v43
	v_fma_f32 v42, -v150, v151, 1.0
	v_rcp_f32_e32 v151, v45
	v_rcp_f32_e32 v47, v46
	global_load_ushort v36, v[36:37], off
	s_waitcnt vmcnt(4)
	v_lshlrev_b32_e32 v38, 16, v38
	v_cndmask_b32_e64 v151, v151, 1.0, s[56:57]
	v_mul_f32_e32 v151, v46, v151
	global_load_ushort v46, v[48:49], off
	v_mul_f32_e32 v150, v45, v47
	v_fma_f32 v45, -v45, v47, 1.0
	s_waitcnt vmcnt(3)
	v_lshlrev_b32_e32 v40, 16, v40
	s_waitcnt vmcnt(2)
	v_lshlrev_b32_e32 v44, 16, v44
	s_waitcnt vmcnt(0)
	v_lshlrev_b32_e32 v47, 16, v46
	v_mul_f32_e32 v47, 0xbfb8aa3b, v47
	v_exp_f32_e32 v47, v47
	global_load_ushort v46, v[148:149], off
	v_min_f32_e32 v47, 0x7149f2ca, v47
	v_add_f32_e32 v48, 1.0, v47
	v_rcp_f32_e32 v49, v48
	v_fma_f32 v47, v183, v47, 1.0
	v_rcp_f32_e32 v148, v47
	v_mul_f32_e32 v152, v47, v49
	v_fma_f32 v47, -v47, v49, 1.0
	v_lshlrev_b32_e32 v49, 16, v36
	v_mul_f32_e32 v36, 0xbfb8aa3b, v38
	v_exp_f32_e32 v36, v36
	v_cndmask_b32_e64 v148, v148, 1.0, s[56:57]
	v_mul_f32_e32 v48, v48, v148
	v_sub_u32_e32 v148, s4, v54
	v_min_f32_e32 v36, 0x7149f2ca, v36
	v_add_f32_e32 v37, 1.0, v36
	v_rcp_f32_e32 v38, v37
	v_fma_f32 v36, v183, v36, 1.0
	v_rcp_f32_e32 v39, v36
	v_mul_f32_e32 v153, v36, v38
	v_fma_f32 v185, -v36, v38, 1.0
	v_subrev_u32_e32 v36, 17, v148
	v_cndmask_b32_e32 v36, v36, v62, vcc
	v_cndmask_b32_e64 v39, v39, 1.0, s[56:57]
	v_add_u32_e32 v36, s60, v36
	v_mul_f32_e32 v184, v37, v39
	v_ashrrev_i32_e32 v37, 31, v36
	v_lshlrev_b64 v[36:37], 11, v[36:37]
	v_lshl_add_u64 v[36:37], v[36:37], 0, v[146:147]
	v_lshlrev_b64 v[36:37], 1, v[36:37]
	v_lshl_add_u64 v[38:39], s[12:13], 0, v[36:37]
	v_lshl_add_u64 v[36:37], s[36:37], 0, v[36:37]
	global_load_ushort v205, v[38:39], off
	global_load_ushort v206, v[36:37], off
	v_subrev_u32_e32 v36, 18, v148
	v_cndmask_b32_e32 v36, v36, v64, vcc
	v_add_u32_e32 v36, s60, v36
	v_ashrrev_i32_e32 v37, 31, v36
	v_lshlrev_b64 v[36:37], 11, v[36:37]
	v_lshl_add_u64 v[36:37], v[36:37], 0, v[146:147]
	v_lshlrev_b64 v[36:37], 1, v[36:37]
	v_lshl_add_u64 v[38:39], s[12:13], 0, v[36:37]
	v_lshl_add_u64 v[36:37], s[36:37], 0, v[36:37]
	global_load_ushort v203, v[38:39], off
	global_load_ushort v204, v[36:37], off
	v_subrev_u32_e32 v36, 19, v148
	v_cndmask_b32_e32 v36, v36, v66, vcc
	v_add_u32_e32 v36, s60, v36
	v_ashrrev_i32_e32 v37, 31, v36
	v_lshlrev_b64 v[36:37], 11, v[36:37]
	v_lshl_add_u64 v[36:37], v[36:37], 0, v[146:147]
	v_lshlrev_b64 v[36:37], 1, v[36:37]
	v_lshl_add_u64 v[38:39], s[12:13], 0, v[36:37]
	v_lshl_add_u64 v[36:37], s[36:37], 0, v[36:37]
	global_load_ushort v201, v[38:39], off
	global_load_ushort v202, v[36:37], off
	v_subrev_u32_e32 v36, 20, v148
	v_cndmask_b32_e32 v36, v36, v68, vcc
	v_add_u32_e32 v36, s60, v36
	v_ashrrev_i32_e32 v37, 31, v36
	v_lshlrev_b64 v[36:37], 11, v[36:37]
	v_lshl_add_u64 v[36:37], v[36:37], 0, v[146:147]
	v_lshlrev_b64 v[36:37], 1, v[36:37]
	v_lshl_add_u64 v[38:39], s[12:13], 0, v[36:37]
	v_lshl_add_u64 v[36:37], s[36:37], 0, v[36:37]
	global_load_ushort v199, v[38:39], off
	global_load_ushort v200, v[36:37], off
	v_sub_u32_e32 v36, s4, v51
	v_subrev_u32_e32 v36, 17, v36
	v_cndmask_b32_e32 v36, v36, v55, vcc
	v_add_u32_e32 v36, s60, v36
	v_ashrrev_i32_e32 v37, 31, v36
	v_lshlrev_b64 v[36:37], 12, v[36:37]
	v_lshl_add_u64 v[36:37], s[0:1], 0, v[36:37]
	v_lshl_add_u64 v[36:37], v[36:37], 0, s[62:63]
	v_lshl_add_u64 v[36:37], v[36:37], 0, v[2:3]
	global_load_dwordx2 v[148:149], v[36:37], off
	v_mul_f32_e32 v36, v41, v150
	v_mul_f32_e32 v37, v36, v152
	v_mul_f32_e32 v39, v43, v151
	v_mul_f32_e32 v38, v37, v153
	v_mul_f32_e32 v48, v39, v48
	v_mul_f32_e32 v150, v48, v184
	ds_bpermute_b32 v2, v57, v38
	ds_bpermute_b32 v151, v57, v150
	s_waitcnt vmcnt(9)
	v_lshlrev_b32_e32 v46, 16, v46
	s_waitcnt lgkmcnt(1)
	v_mul_f32_e32 v2, v38, v2
	v_cndmask_b32_e64 v2, v38, v2, s[40:41]
	s_waitcnt lgkmcnt(0)
	v_mul_f32_e32 v151, v150, v151
	v_cndmask_b32_e64 v151, v150, v151, s[40:41]
	ds_bpermute_b32 v152, v59, v2
	ds_bpermute_b32 v153, v59, v151
	s_waitcnt lgkmcnt(1)
	v_mul_f32_e32 v152, v2, v152
	v_cndmask_b32_e64 v2, v2, v152, s[42:43]
	s_waitcnt lgkmcnt(0)
	v_mul_f32_e32 v152, v151, v153
	v_cndmask_b32_e64 v151, v151, v152, s[42:43]
	ds_bpermute_b32 v152, v57, v2
	ds_bpermute_b32 v151, v57, v151
	ds_bpermute_b32 v2, v61, v2
	s_waitcnt lgkmcnt(2)
	v_cndmask_b32_e64 v152, 1.0, v152, s[40:41]
	s_waitcnt lgkmcnt(1)
	v_cndmask_b32_e64 v151, 1.0, v151, s[40:41]
	v_mul_f32_e32 v43, v43, v151
	v_mul_f32_e32 v41, v41, v152
	v_min_f32_e32 v43, 0x799a130c, v43
	v_mul_f32_e32 v40, v41, v40
	v_mul_f32_e32 v42, v42, v43
	v_cvt_pk_bf16_f32 v40, v40, s0
	ds_write_b16 v141, v40
	v_cvt_pk_bf16_f32 v40, v42, s0
	v_mul_f32_e32 v39, v39, v151
	v_mul_f32_e32 v36, v36, v152
	ds_write_b16 v141, v40 offset:4352
	s_waitcnt lgkmcnt(2)
	v_mul_f32_e32 v40, v42, v2
	v_min_f32_e32 v39, 0x799a130c, v39
	v_mul_f32_e32 v36, v36, v44
	v_cvt_pk_bf16_f32 v40, v40, s0
	v_mul_f32_e32 v39, v45, v39
	v_cvt_pk_bf16_f32 v36, v36, s0
	ds_write_b16 v170, v40 offset:8704
	ds_write_b16 v143, v36
	v_cvt_pk_bf16_f32 v36, v39, s0
	ds_write_b16 v143, v36 offset:4352
	v_mul_f32_e32 v36, v39, v2
	v_cvt_pk_bf16_f32 v36, v36, s0
	ds_write_b16 v170, v36 offset:8706
	v_mul_f32_e32 v36, v48, v151
	v_mul_f32_e32 v37, v37, v152
	v_min_f32_e32 v36, 0x799a130c, v36
	v_mul_f32_e32 v37, v37, v46
	v_mul_f32_e32 v36, v47, v36
	v_cvt_pk_bf16_f32 v37, v37, s0
	ds_write_b16 v172, v37
	v_cvt_pk_bf16_f32 v37, v36, s0
	v_mul_f32_e32 v36, v36, v2
	v_cvt_pk_bf16_f32 v36, v36, s0
	ds_write_b16 v172, v37 offset:4352
	ds_write_b16 v170, v36 offset:8708
	v_mul_f32_e32 v36, v150, v151
	v_mul_f32_e32 v37, v38, v152
	v_min_f32_e32 v36, 0x799a130c, v36
	v_mul_f32_e32 v37, v37, v49
	v_mul_f32_e32 v36, v185, v36
	v_cvt_pk_bf16_f32 v37, v37, s0
	ds_write_b16 v174, v37
	v_cvt_pk_bf16_f32 v37, v36, s0
	v_mul_f32_e32 v36, v36, v2
	v_cvt_pk_bf16_f32 v36, v36, s0
	ds_write_b16 v174, v37 offset:4352
	ds_write_b16 v170, v36 offset:8710
	s_and_saveexec_b64 s[14:15], s[44:45]
	ds_write_b32 v65, v2 offset:20992
	s_or_b64 exec, exec, s[14:15]
	s_lshr_b32 s61, s4, 4
	s_add_u32 s14, s18, s80
	s_addc_u32 s15, s19, 0
	v_lshl_add_u64 v[150:151], v[136:137], 0, s[62:63]
	s_add_u32 s62, s14, s62
	s_addc_u32 s80, s15, 0
	s_lshl_b64 s[14:15], s[20:21], 1
	s_add_u32 s14, s62, s14
	s_addc_u32 s15, s80, s15
	v_lshlrev_b32_e32 v2, 1, v50
	v_lshl_add_u64 v[152:153], s[14:15], 0, v[2:3]
	v_add_u32_e32 v197, s4, v180
	v_add_u32_e32 v198, s4, v181
	s_mov_b32 s62, 0
	s_sub_i32 s80, 0, s61
	s_mov_b32 s81, 2
	ds_write_b16 v69, v0 offset:14848
	ds_write_b16_d16_hi v69, v0 offset:14896
	ds_write_b16 v69, v1 offset:14944
	ds_write_b16_d16_hi v69, v1 offset:14992
	v_mov_b32_e32 v208, 0
	v_mov_b32_e32 v209, 0
	v_mov_b32_e32 v210, 0
	v_mov_b32_e32 v211, 0
	v_mov_b32_e32 v212, 0x580
	v_mad_u32_u24 v207, v155, v212, v63
	s_and_saveexec_b64 s[14:15], s[46:47]
	ds_write_b128 v207, v[208:211] offset:8736
	s_or_b64 exec, exec, s[14:15]
	v_mov_b32_e32 v0, v54
	v_sub_u32_e32 v1, 1023, v0
	v_cndmask_b32_e32 v0, v1, v0, vcc
	v_add_u32_e32 v0, s60, v0
	v_lshlrev_b32_e32 v0, 12, v0
	v_lshl_add_u32 v197, v146, 1, v0
	v_add_u32_e32 v0, 1, v54
	v_sub_u32_e32 v1, 1023, v0
	v_cndmask_b32_e32 v0, v1, v0, vcc
	v_add_u32_e32 v0, s60, v0
	v_lshlrev_b32_e32 v0, 12, v0
	v_lshl_add_u32 v198, v146, 1, v0
	v_add_u32_e32 v0, 2, v54
	v_sub_u32_e32 v1, 1023, v0
	v_cndmask_b32_e32 v0, v1, v0, vcc
	v_add_u32_e32 v0, s60, v0
	v_lshlrev_b32_e32 v0, 12, v0
	v_lshl_add_u32 v178, v146, 1, v0
	v_add_u32_e32 v0, 3, v54
	v_sub_u32_e32 v1, 1023, v0
	v_cndmask_b32_e32 v0, v1, v0, vcc
	v_add_u32_e32 v0, s60, v0
	v_lshlrev_b32_e32 v0, 12, v0
	v_lshl_add_u32 v179, v146, 1, v0
	v_readfirstlane_b32 s100, v152
	v_readfirstlane_b32 s101, v153
	v_readfirstlane_b32 s32, v146
	s_lshl_b32 s32, s32, 1
	s_sub_u32 s100, s100, s32
	s_subb_u32 s101, s101, 0
	v_add_u32_e32 v0, 32, v51
	v_sub_u32_e32 v1, 1023, v0
	v_cndmask_b32_e32 v0, v1, v0, vcc
	v_add_u32_e32 v0, s60, v0
	v_lshlrev_b32_e32 v0, 12, v0
	v_mov_b32_e32 v1, 0
	v_lshl_add_u64 v[150:151], v[0:1], 0, v[150:151]
	s_cmp_lg_u64 vcc, 0
	s_mov_b32 s32, 0x10000
	s_cselect_b32 s32, s32, 0xffff0000
	s_cbranch_scc0 .Lhg_bwd_l
	s_add_u32 s12, s12, 0x20000
	s_addc_u32 s13, s13, 0
	s_add_u32 s98, s36, 0x20000
	s_addc_u32 s99, s37, 0
	s_branch .Lhg_dir_l
.Lhg_bwd_l:
	s_sub_u32 s12, s12, 0x20000
	s_subb_u32 s13, s13, 0
	s_sub_u32 s98, s36, 0x20000
	s_subb_u32 s99, s37, 0
.Lhg_dir_l:
	v_mov_b32_e32 v146, s32
	v_ashrrev_i32_e32 v147, 31, v146
	s_waitcnt vmcnt(0) lgkmcnt(0)
	v_mov_b32_e32 v157, v199
	v_mov_b32_e32 v159, v200
	v_mov_b32_e32 v161, v201
	v_mov_b32_e32 v163, v202
	v_mov_b32_e32 v166, v203
	v_mov_b32_e32 v167, v204
	v_mov_b32_e32 v168, v205
	v_mov_b32_e32 v169, v206
	v_mov_b64_e32 v[164:165], v[148:149]
	s_barrier
	s_branch .LBB0_979
.LBB0_979:
	s_bitcmp1_b32 s81, 0
	s_cselect_b32 s82, 0x5800, 0
	s_add_i32 s14, s81, -1
	s_cmp_ge_u32 s14, s61
	s_cbranch_scc1 .LBB0_985
	s_cmp_ge_u32 s81, s61
	s_waitcnt vmcnt(4)
	v_mov_b32_e32 v199, v157
	v_mov_b32_e32 v200, v159
	v_mov_b32_e32 v201, v161
	v_mov_b32_e32 v202, v163
	v_mov_b32_e32 v203, v166
	v_mov_b32_e32 v204, v167
	v_mov_b32_e32 v205, v168
	v_mov_b32_e32 v206, v169
	v_mov_b64_e32 v[148:149], v[164:165]
	s_cbranch_scc1 .LBB0_982
	global_load_ushort v168, v197, s[12:13]
	global_load_ushort v169, v197, s[98:99]
	global_load_ushort v166, v198, s[12:13]
	global_load_ushort v167, v198, s[98:99]
	global_load_ushort v161, v178, s[12:13]
	global_load_ushort v163, v178, s[98:99]
	global_load_ushort v157, v179, s[12:13]
	global_load_ushort v159, v179, s[98:99]
	global_load_dwordx2 v[164:165], v[150:151], off

.LBB0_985:
	v_lshlrev_b32_e32 v0, 1, v135
	v_lshlrev_b32_e32 v1, 1, v154
	v_add3_u32 v2, s82, v0, v1
	v_add_u32_e32 v207, s82, v63
	v_lshl_add_u32 v227, v54, 1, v207
	v_add_u32_e32 v0, v2, v176
	ds_read_b128 v[36:39], v2 offset:4352
	ds_read_b128 v[40:43], v2
	ds_read_b128 v[208:211], v2 offset:4416
	ds_read_b128 v[184:187], v2 offset:64
	ds_read_b128 v[212:215], v2 offset:4480
	ds_read_b128 v[228:231], v2 offset:128
	ds_read_b128 v[232:235], v2 offset:4544
	ds_read_b128 v[236:239], v2 offset:192
	ds_read_b64 v[188:189], v227 offset:14848
	ds_read2_b64 v[240:243], v0 offset1:4
	ds_read2_b64 v[244:247], v0 offset0:8 offset1:12
	s_and_b64 s[14:15], s[54:55], s[52:53]
	v_mov_b32_e32 v190, v3
	v_mov_b32_e32 v191, v3
	s_waitcnt lgkmcnt(9)
	v_mfma_f32_16x16x32_bf16 v[36:39], v[36:39], v[40:43], 0
	s_waitcnt lgkmcnt(7)
	v_mfma_f32_16x16x32_bf16 v[36:39], v[208:211], v[184:187], v[36:39]
	s_waitcnt lgkmcnt(5)
	v_mfma_f32_16x16x32_bf16 v[36:39], v[212:215], v[228:231], v[36:39]
	s_waitcnt lgkmcnt(3)
	v_mfma_f32_16x16x32_bf16 v[36:39], v[232:235], v[236:239], v[36:39]
	ds_read2_b64 v[208:211], v0 offset0:16 offset1:20
	ds_read2_b64 v[212:215], v0 offset0:24 offset1:28
	v_cvt_pk_bf16_f32 v184, v4, v5
	v_cvt_pk_bf16_f32 v185, v6, v7
	v_cvt_pk_bf16_f32 v186, v8, v9
	v_cvt_pk_bf16_f32 v187, v10, v11
	v_mov_b32_e32 v2, v3
	s_nop 0
	v_cndmask_b32_e64 v192, v38, 0, s[14:15]
	s_and_b64 s[14:15], s[14:15], s[50:51]
	v_cndmask_b32_e64 v0, v37, 0, s[14:15]
	s_and_b64 s[14:15], s[14:15], s[48:49]
	v_cndmask_b32_e64 v36, v36, 0, s[14:15]
	v_cndmask_b32_e64 v1, v39, 0, s[54:55]
	v_cvt_pk_bf16_f32 v0, v36, v0
	v_cvt_pk_bf16_f32 v1, v192, v1
	s_nop 0
	s_waitcnt lgkmcnt(4)
	v_mfma_f32_16x16x32_bf16 v[36:39], v[0:3], v[188:191], 0
	v_cvt_pk_bf16_f32 v40, v12, v13
	v_cvt_pk_bf16_f32 v41, v14, v15
	v_cvt_pk_bf16_f32 v42, v16, v17
	v_cvt_pk_bf16_f32 v43, v18, v19
	v_cvt_pk_bf16_f32 v228, v20, v21
	v_cvt_pk_bf16_f32 v229, v22, v23
	v_cvt_pk_bf16_f32 v230, v24, v25
	v_cvt_pk_bf16_f32 v231, v26, v27
	v_cvt_pk_bf16_f32 v232, v28, v29
	v_cvt_pk_bf16_f32 v233, v30, v31
	v_cvt_pk_bf16_f32 v234, v32, v33
	v_cvt_pk_bf16_f32 v235, v34, v35
	s_waitcnt lgkmcnt(3)
	v_mfma_f32_16x16x32_bf16 v[36:39], v[240:243], v[184:187], v[36:39]
	s_waitcnt lgkmcnt(2)
	v_mfma_f32_16x16x32_bf16 v[36:39], v[244:247], v[40:43], v[36:39]
	s_waitcnt lgkmcnt(1)
	v_mfma_f32_16x16x32_bf16 v[36:39], v[208:211], v[228:231], v[36:39]
	s_waitcnt lgkmcnt(0)
	v_mfma_f32_16x16x32_bf16 v[36:39], v[212:215], v[232:235], v[36:39]
	v_add_u32_e32 v227, v207, v155
	v_lshl_add_u32 v216, v54, 2, s82
	v_add3_u32 v217, s82, v155, v156
	v_mov_b32_e32 v44, 0
	v_mov_b32_e32 v45, 0
	v_mov_b32_e32 v46, 0
	v_mov_b32_e32 v47, 0
	s_and_saveexec_b64 s[14:15], s[46:47]
	ds_read_b128 v[44:47], v227 offset:14848
	s_or_b64 exec, exec, s[14:15]
	ds_read_b128 v[240:243], v216 offset:20992
	ds_read_b128 v[184:187], v217 offset:8704
	ds_read_b128 v[244:247], v216 offset:21056
	ds_read_b128 v[40:43], v217 offset:9472
	ds_read_b128 v[208:211], v216 offset:21120
	ds_read_b128 v[228:231], v217 offset:10240
	ds_read_b128 v[212:215], v216 offset:21184
	ds_read_b128 v[232:235], v217 offset:11008
	v_cvt_pk_bf16_f32 v192, v36, s0
	global_store_short v197, v192, s[100:101]
	v_cvt_pk_bf16_f32 v193, v37, s0
	global_store_short v198, v193, s[100:101]
	v_cvt_pk_bf16_f32 v192, v38, s0
	global_store_short v178, v192, s[100:101]
	v_cvt_pk_bf16_f32 v193, v39, s0
	global_store_short v179, v193, s[100:101]
	v_add_u32_e32 v197, s32, v197
	v_add_u32_e32 v198, s32, v198
	v_add_u32_e32 v178, s32, v178
	v_add_u32_e32 v179, s32, v179
	v_lshl_add_u64 v[150:151], v[150:151], 0, v[146:147]
	s_waitcnt lgkmcnt(6)
	v_pk_mul_f32 v[6:7], v[6:7], v[242:243]
	v_pk_mul_f32 v[4:5], v[4:5], v[240:241]
	s_nop 1
	v_mfma_f32_16x16x32_bf16 v[4:7], v[184:187], v[44:47], v[4:7]
	ds_read_b128 v[240:243], v216 offset:21248
	ds_read_b128 v[184:187], v217 offset:11776
	s_waitcnt lgkmcnt(6)
	v_pk_mul_f32 v[10:11], v[10:11], v[246:247]
	v_pk_mul_f32 v[8:9], v[8:9], v[244:245]
	s_nop 1
	v_mfma_f32_16x16x32_bf16 v[8:11], v[40:43], v[44:47], v[8:11]
	ds_read_b128 v[244:247], v216 offset:21312
	ds_read_b128 v[40:43], v217 offset:12544
	s_waitcnt lgkmcnt(6)
	v_pk_mul_f32 v[14:15], v[14:15], v[210:211]
	v_pk_mul_f32 v[12:13], v[12:13], v[208:209]
	s_nop 1
	v_mfma_f32_16x16x32_bf16 v[12:15], v[228:231], v[44:47], v[12:15]
	ds_read_b128 v[208:211], v216 offset:21376
	ds_read_b128 v[228:231], v217 offset:13312
	s_waitcnt lgkmcnt(6)
	v_pk_mul_f32 v[18:19], v[18:19], v[214:215]
	v_pk_mul_f32 v[16:17], v[16:17], v[212:213]
	s_nop 1
	v_mfma_f32_16x16x32_bf16 v[16:19], v[232:235], v[44:47], v[16:19]
	ds_read_b128 v[212:215], v216 offset:21440
	ds_read_b128 v[232:235], v217 offset:14080
	s_waitcnt lgkmcnt(6)
	v_pk_mul_f32 v[22:23], v[22:23], v[242:243]
	v_pk_mul_f32 v[20:21], v[20:21], v[240:241]
	s_nop 1
	v_mfma_f32_16x16x32_bf16 v[20:23], v[184:187], v[44:47], v[20:23]
	s_waitcnt lgkmcnt(4)
	v_pk_mul_f32 v[26:27], v[26:27], v[246:247]
	v_pk_mul_f32 v[24:25], v[24:25], v[244:245]
	s_nop 1
	v_mfma_f32_16x16x32_bf16 v[24:27], v[40:43], v[44:47], v[24:27]
	s_waitcnt lgkmcnt(2)
	v_pk_mul_f32 v[30:31], v[30:31], v[210:211]
	v_pk_mul_f32 v[28:29], v[28:29], v[208:209]
	s_nop 1
	v_mfma_f32_16x16x32_bf16 v[28:31], v[228:231], v[44:47], v[28:31]
	s_waitcnt lgkmcnt(0)
	v_pk_mul_f32 v[34:35], v[34:35], v[214:215]
	v_pk_mul_f32 v[32:33], v[32:33], v[212:213]
	s_nop 1
	v_mfma_f32_16x16x32_bf16 v[32:35], v[232:235], v[44:47], v[32:35]
	s_add_i32 s81, s81, 1
	s_add_i32 s62, s62, 16
	s_add_i32 s14, s80, s81
	s_cmp_eq_u32 s14, 2
	s_barrier
	s_cbranch_scc1 .LBB0_1003
	s_branch .LBB0_979

	.amdhsa_kernel _Z10fwd_kernel4Args
		.amdhsa_group_segment_fixed_size 0
		.amdhsa_private_segment_fixed_size 0
		.amdhsa_kernarg_size 560
		.amdhsa_user_sgpr_count 2
		.amdhsa_user_sgpr_dispatch_ptr 0
		.amdhsa_user_sgpr_queue_ptr 0
		.amdhsa_user_sgpr_kernarg_segment_ptr 1
		.amdhsa_user_sgpr_dispatch_id 0
		.amdhsa_user_sgpr_kernarg_preload_length 0
		.amdhsa_user_sgpr_kernarg_preload_offset 0
		.amdhsa_user_sgpr_private_segment_size 0
		.amdhsa_uses_dynamic_stack 0
		.amdhsa_enable_private_segment 0
		.amdhsa_system_sgpr_workgroup_id_x 1
		.amdhsa_system_sgpr_workgroup_id_y 0
		.amdhsa_system_sgpr_workgroup_id_z 0
		.amdhsa_system_sgpr_workgroup_info 0
		.amdhsa_system_vgpr_workitem_id 0
		.amdhsa_next_free_vgpr 256
		.amdhsa_next_free_sgpr 102
		.amdhsa_accum_offset 256
		.amdhsa_reserve_vcc 1
		.amdhsa_float_round_mode_32 0
		.amdhsa_float_round_mode_16_64 0
		.amdhsa_float_denorm_mode_32 3
		.amdhsa_float_denorm_mode_16_64 3
		.amdhsa_dx10_clamp 1
		.amdhsa_ieee_mode 1
		.amdhsa_fp16_overflow 0
		.amdhsa_tg_split 0
		.amdhsa_exception_fp_ieee_invalid_op 0
		.amdhsa_exception_fp_denorm_src 0
		.amdhsa_exception_fp_ieee_div_zero 0
		.amdhsa_exception_fp_ieee_overflow 0
		.amdhsa_exception_fp_ieee_underflow 0
		.amdhsa_exception_fp_ieee_inexact 0
		.amdhsa_exception_int_div_zero 0
	.end_amdhsa_kernel

amdhsa.kernels:
  - .agpr_count:     0
    .args:
      - .offset:         0
        .size:           304
        .value_kind:     by_value
      - .offset:         304
        .size:           4
        .value_kind:     hidden_block_count_x
      - .offset:         308
        .size:           4
        .value_kind:     hidden_block_count_y
      - .offset:         312
        .size:           4
        .value_kind:     hidden_block_count_z
      - .offset:         316
        .size:           2
        .value_kind:     hidden_group_size_x
      - .offset:         318
        .size:           2
        .value_kind:     hidden_group_size_y
      - .offset:         320
        .size:           2
        .value_kind:     hidden_group_size_z
      - .offset:         322
        .size:           2
        .value_kind:     hidden_remainder_x
      - .offset:         324
        .size:           2
        .value_kind:     hidden_remainder_y
      - .offset:         326
        .size:           2
        .value_kind:     hidden_remainder_z
      - .offset:         344
        .size:           8
        .value_kind:     hidden_global_offset_x
      - .offset:         352
        .size:           8
        .value_kind:     hidden_global_offset_y
      - .offset:         360
        .size:           8
        .value_kind:     hidden_global_offset_z
      - .offset:         368
        .size:           2
        .value_kind:     hidden_grid_dims
      - .offset:         424
        .size:           4
        .value_kind:     hidden_dynamic_lds_size
    .group_segment_fixed_size: 0
    .kernarg_segment_align: 8
    .kernarg_segment_size: 560
    .language:       OpenCL C
    .language_version:
      - 2
      - 0
    .max_flat_workgroup_size: 512
    .name:           _Z10fwd_kernel4Args
    .private_segment_fixed_size: 0
    .sgpr_count:     108
    .sgpr_spill_count: 299
    .symbol:         _Z10fwd_kernel4Args.kd
    .uniform_work_group_size: 1
    .uses_dynamic_stack: false
    .vgpr_count:     256
    .vgpr_spill_count: 0
    .wavefront_size: 64
